# opt32: opt26 with tile sa+2's V LDS-DMA pair issued at the start of tile b's softmax, K pair between tiles
# speedup vs baseline: 1.0092x; 1.0092x over previous
; template <bool SWA>
; __device__ __forceinline__ void unit(LAS unsigned char* lds, const bf16_t* PROJ, const bf16_t* KT, const bf16_t* VT, bf16_t* OB, int opitch, int ocol, int b, int head, int qb, float slope2, float m_init, float lam, const float* subg) {
;     ...
;         if (acta) { SM_T(s0, s1, kva, clsa); if (pvalid) PV_TILE(sa); }
;         if (actb) { SM_T(u0, u1, kvb, clsb); if (pvalid) PV_TILE(sb); }
.LBB0_903:
	s_add_i32 s29, s1, -3
	s_add_i32 s30, s1, -1
	s_cmp_lt_u32 s29, s0
	s_cselect_b32 s30, s29, s30
	s_lshl_b32 s30, s30, 14
	s_add_i32 s31, s25, 0xffffc000
	s_and_b32 s31, s31, 0x8000
	s_add_u32 s98, s73, s30
	s_addc_u32 s99, s17, 0
	s_add_i32 s92, s31, s33
	s_mov_b32 m0, s92
	s_nop 0
	global_load_lds_dwordx4 v164, s[98:99]
	s_add_i32 m0, s92, 0x400
	s_nop 0
	global_load_lds_dwordx4 v170, s[98:99]
	v_or_b32_e32 v96, s28, v187
	v_sub_u32_e32 v96, v188, v96
	v_cvt_f32_i32_e32 v96, v96
	s_mov_b64 s[6:7], -1
	s_and_b64 vcc, exec, s[80:81]
	s_cbranch_vccz .LBB0_909
	s_andn2_b64 vcc, exec, s[78:79]
	s_cbranch_vccnz .LBB0_906
	v_mul_f32_e64 v97, -s76, v96
	v_fma_f32 v98, -s76, v96, v194
	s_mov_b64 s[6:7], 0

.LBB0_911:
	s_add_i32 s29, s1, -3
	s_add_i32 s30, s1, -1
	s_cmp_lt_u32 s29, s0
	s_cselect_b32 s30, s29, s30
	s_lshl_b32 s30, s30, 14
	s_add_i32 s31, s25, 0xffffc000
	s_and_b32 s31, s31, 0x8000
	s_add_u32 s98, s2, s30
	s_addc_u32 s99, s23, 0
	s_add_i32 s92, s31, s72
	s_mov_b32 m0, s92
	s_nop 0
	global_load_lds_dwordx4 v168, s[98:99]
	s_add_i32 m0, s92, 0x400
	s_nop 0
	global_load_lds_dwordx4 v172, s[98:99]
	v_max_f32_e32 v96, v80, v81
	v_max_f32_e32 v99, v64, v65
	v_max3_f32 v96, v96, v82, v83
	v_max3_f32 v99, v99, v66, v67
	v_max3_f32 v96, v96, v84, v85
	v_max3_f32 v99, v99, v68, v69
	v_max3_f32 v96, v96, v86, v87
	v_max3_f32 v99, v99, v70, v71
	v_max3_f32 v96, v96, v88, v89
	v_max3_f32 v99, v99, v72, v73
	v_max3_f32 v96, v96, v90, v91
	v_max3_f32 v99, v99, v74, v75
	v_max3_f32 v96, v96, v92, v93
	v_max3_f32 v99, v99, v76, v77
	v_max3_f32 v96, v96, v94, v95
	v_max3_f32 v99, v99, v78, v79
	v_add_f32_e32 v96, v97, v96
	v_add_f32_e32 v99, v98, v99
	v_max_f32_e32 v96, v96, v99
	v_mov_b32_e32 v99, v96
	s_nop 1
	v_permlane32_swap_b32_e32 v96, v99
	v_max_f32_e32 v96, v96, v99
	v_sub_f32_e32 v99, v96, v174
	v_cmp_gt_f32_e32 vcc, s18, v99
	s_cmp_lg_u64 vcc, exec
	s_cselect_b64 s[78:79], -1, 0
	s_cmp_eq_u64 vcc, exec
	s_cbranch_scc1 .LBB0_915
	v_max_f32_e32 v203, v174, v96
	v_sub_f32_e32 v96, v174, v203
	v_exp_f32_e32 v96, v96
	s_nop 0
	v_cmp_neq_f32_e32 vcc, 1.0, v96
	s_cbranch_vccz .LBB0_914
	v_mul_f32_e32 v30, v96, v30
	v_mul_f32_e32 v31, v96, v31
	v_mul_f32_e32 v28, v96, v28
	v_mul_f32_e32 v29, v96, v29
	v_mul_f32_e32 v26, v96, v26
	v_mul_f32_e32 v27, v96, v27
	v_mul_f32_e32 v24, v96, v24
	v_mul_f32_e32 v25, v96, v25
	v_mul_f32_e32 v22, v96, v22
	v_mul_f32_e32 v23, v96, v23
	v_mul_f32_e32 v20, v96, v20
	v_mul_f32_e32 v21, v96, v21
	v_mul_f32_e32 v18, v96, v18
	v_mul_f32_e32 v19, v96, v19
	v_mul_f32_e32 v16, v96, v16
	v_mul_f32_e32 v17, v96, v17
	v_mul_f32_e32 v62, v96, v62
	v_mul_f32_e32 v63, v96, v63
	v_mul_f32_e32 v60, v96, v60
	v_mul_f32_e32 v61, v96, v61
	v_mul_f32_e32 v58, v96, v58
	v_mul_f32_e32 v59, v96, v59
	v_mul_f32_e32 v56, v96, v56
	v_mul_f32_e32 v57, v96, v57
	v_mul_f32_e32 v54, v96, v54
	v_mul_f32_e32 v55, v96, v55
	v_mul_f32_e32 v52, v96, v52
	v_mul_f32_e32 v53, v96, v53
	v_mul_f32_e32 v50, v96, v50
	v_mul_f32_e32 v51, v96, v51
	v_mul_f32_e32 v48, v96, v48
	v_mul_f32_e32 v49, v96, v49
	v_mul_f32_e32 v46, v96, v46
	v_mul_f32_e32 v47, v96, v47
	v_mul_f32_e32 v44, v96, v44
	v_mul_f32_e32 v45, v96, v45
	v_mul_f32_e32 v42, v96, v42
	v_mul_f32_e32 v43, v96, v43
	v_mul_f32_e32 v40, v96, v40
	v_mul_f32_e32 v41, v96, v41
	v_mul_f32_e32 v38, v96, v38
	v_mul_f32_e32 v39, v96, v39
	v_mul_f32_e32 v36, v96, v36
	v_mul_f32_e32 v37, v96, v37
	v_mul_f32_e32 v34, v96, v34
	v_mul_f32_e32 v35, v96, v35
	v_mul_f32_e32 v32, v96, v32
	v_mul_f32_e32 v33, v96, v33
	v_mul_f32_e32 v14, v96, v14
	v_mul_f32_e32 v15, v96, v15
	v_mul_f32_e32 v12, v96, v12
	v_mul_f32_e32 v13, v96, v13
	v_mul_f32_e32 v10, v96, v10
	v_mul_f32_e32 v11, v96, v11
	v_mul_f32_e32 v8, v96, v8
	v_mul_f32_e32 v9, v96, v9
	v_mul_f32_e32 v6, v96, v6
	v_mul_f32_e32 v7, v96, v7
	v_mul_f32_e32 v4, v96, v4
	v_mul_f32_e32 v5, v96, v5
	v_mul_f32_e32 v2, v96, v2
	v_mul_f32_e32 v3, v96, v3
	v_mul_f32_e32 v0, v96, v0
	v_mul_f32_e32 v1, v96, v1
